# as S12 with first V-fragment reads and the LDS-DMA address arithmetic and issues all packed into the first five QK MFMA gaps
# baseline (speedup 1.0000x reference)
; #define SBAR() __builtin_amdgcn_sched_barrier(0)
; __device__ __forceinline__ void finishSM(f32x16& p0, f32x16& p1, float alpha, float& l_reg, bf16x8& pa0, bf16x8& pa1, bf16x8& pa2, bf16x8& pa3) {
;   for (int r = 0; r < 16; ++r) p1[r] = __builtin_amdgcn_exp2f(p1[r]);
;   float ps = 0; for (int r = 0; r < 16; ++r) ps += p0[r]; for (int r = 0; r < 16; ++r) ps += p1[r];
;   { auto rr = __builtin_amdgcn_permlane32_swap(__float_as_uint(ps), __float_as_uint(ps), false, false);
;     ps = __uint_as_float(rr[0]) + __uint_as_float(rr[1]); }
;   l_reg = l_reg * alpha + ps;
;     ...
;   PK4(p0, 0, pa0); PK4(p0, 8, pa1); PK4(p1, 0, pa2); PK4(p1, 8, pa3);
;     ...
; }
; __device__ __forceinline__ void kload(bf16x8 (&kf)[8], const char* Ks, int r32, int hi, int sb) {
; #pragma unroll
;   for (int d0 = 0; d0 < 4; ++d0) { const int cb = sb + (d0 * 16 + hi * 8) * 2;
;     kf[2 * d0] = *reinterpret_cast<const bf16x8*>(Ks + KSWZ(r32, cb)); kf[2 * d0 + 1] = *reinterpret_cast<const bf16x8*>(Ks + KSWZ(32 + r32, cb)); }
; }
; __device__ __forceinline__ void kmma(f32x16& p0, f32x16& p1, const bf16x8 (&kf)[8], const bf16x8* qr) {
;   asm volatile("s_waitcnt lgkmcnt(0)" ::: "memory"); SBAR();
;   p0 = f32x16{}; p1 = f32x16{};
; #pragma unroll
;   for (int d0 = 0; d0 < 4; ++d0) { p0 = __builtin_amdgcn_mfma_f32_32x32x16_bf16(kf[2 * d0], qr[d0], p0, 0, 0, 0); p1 = __builtin_amdgcn_mfma_f32_32x32x16_bf16(kf[2 * d0 + 1], qr[d0], p1, 0, 0, 0); }
; }
.LBB0_770:
	ds_read_b128 v[82:85], v245
	ds_read_b128 v[86:89], v245 offset:8192
	ds_read_b128 v[130:133], v246
	ds_read_b128 v[134:137], v246 offset:8192
	ds_read_b128 v[206:209], v247
	ds_read_b128 v[210:213], v247 offset:8192
	ds_read_b128 v[214:217], v255
	ds_read_b128 v[218:221], v255 offset:8192
	v_exp_f32_e32 v148, v66
	v_add_f32_e32 v66, 0, v175
	v_add_f32_e32 v66, v177, v66
	v_add_f32_e32 v66, v192, v66
	v_add_f32_e32 v66, v195, v66
	v_add_f32_e32 v66, v196, v66
	v_add_f32_e32 v66, v199, v66
	v_add_f32_e32 v66, v200, v66
	v_add_f32_e32 v66, v203, v66
	v_add_f32_e32 v66, v176, v66
	v_add_f32_e32 v66, v193, v66
	v_add_f32_e32 v66, v194, v66
	v_add_f32_e32 v66, v197, v66
	v_add_f32_e32 v66, v198, v66
	v_exp_f32_e32 v149, v67
	v_add_f32_e32 v66, v201, v66
	s_waitcnt lgkmcnt(7)
	v_mfma_f32_32x32x16_bf16 v[98:113], v[82:85], v[126:129], 0
	s_and_b32 s13, s36, 0xc000
	v_exp_f32_e32 v150, v68
	v_add_u32_e32 v244, s13, v164
	v_add_f32_e32 v66, v202, v66
	ds_read_b64_tr_b16 v[228:229], v244 offset:0
	v_exp_f32_e32 v151, v69
	ds_read_b64_tr_b16 v[230:231], v244 offset:0x800
	v_add_f32_e32 v66, v204, v66
	ds_read_b64_tr_b16 v[232:233], v244 offset:0x1000
	ds_read_b64_tr_b16 v[234:235], v244 offset:0x1800
	ds_read_b64_tr_b16 v[236:237], v244 offset:0x2000
	ds_read_b64_tr_b16 v[238:239], v244 offset:0x2800
	ds_read_b64_tr_b16 v[240:241], v244 offset:0x3000
	ds_read_b64_tr_b16 v[242:243], v244 offset:0x3800
	s_waitcnt lgkmcnt(14)
	v_mfma_f32_32x32x16_bf16 v[82:97], v[86:89], v[126:129], 0
	s_add_i32 s37, s12, 2
	v_exp_f32_e32 v186, v70
	s_cmpk_lt_u32 s12, 0x7e
	v_add_f32_e32 v66, v148, v66
	s_cselect_b64 s[0:1], -1, 0
	v_exp_f32_e32 v187, v71
	s_and_b64 s[10:11], s[0:1], exec
	v_add_f32_e32 v66, v149, v66
	s_cselect_b32 s10, 0, 0xffffff80
	v_exp_f32_e32 v188, v72
	s_add_i32 s58, s37, s10
	s_and_b64 s[0:1], s[0:1], exec
	s_cselect_b32 s1, s9, s30
	s_cselect_b32 s0, s8, s26
	s_lshl_b64 s[10:11], s[58:59], 17
	s_waitcnt lgkmcnt(13)
	v_mfma_f32_32x32x16_bf16 v[98:113], v[130:133], v[122:125], v[98:113]
	s_lshl_b64 s[0:1], s[0:1], 11
	v_add_f32_e32 v66, v150, v66
	s_add_u32 s10, s10, s0
	v_exp_f32_e32 v189, v73
	s_addc_u32 s11, s11, s1
	v_add_f32_e32 v66, v151, v66
	s_add_u32 s0, s20, s10
	v_exp_f32_e32 v205, v74
	s_addc_u32 s1, s21, s11
	s_add_u32 s10, s22, s10
	s_addc_u32 s11, s23, s11
	s_and_b32 s13, s37, 0xff
	s_mulk_i32 s13, 0xab
	s_lshr_b32 s13, s13, 9
	s_waitcnt lgkmcnt(12)
	v_mfma_f32_32x32x16_bf16 v[82:97], v[134:137], v[122:125], v[82:97]
	s_mul_i32 s13, s13, 3
	v_add_f32_e32 v66, v186, v66
	s_sub_i32 s13, s37, s13
	v_exp_f32_e32 v222, v75
	s_and_b32 s13, s13, 0xff
	v_add_f32_e32 v66, v187, v66
	s_lshl_b32 s13, s13, 14
	s_mov_b32 s100, s13
	v_exp_f32_e32 v223, v76
	s_add_i32 s42, s36, 0xffffc000
	v_add_f32_e32 v66, v188, v66
	s_and_b32 s42, s42, 0xc000
	s_add_i32 s13, s13, s27
	s_add_i32 s42, s42, s31
	v_lshl_add_u64 v[246:247], s[0:1], 0, v[146:147]
	s_mov_b32 m0, s13
	s_waitcnt lgkmcnt(11)
	v_mfma_f32_32x32x16_bf16 v[98:113], v[206:209], v[118:121], v[98:113]
	global_load_lds_dwordx4 v[246:247], off
	v_exp_f32_e32 v224, v77
	v_lshl_add_u64 v[246:247], s[10:11], 0, v[142:143]
	v_add_f32_e32 v66, v189, v66
	s_mov_b32 m0, s42
	v_exp_f32_e32 v225, v78
	global_load_lds_dwordx4 v[246:247], off
	v_add_f32_e32 v66, v205, v66
	v_lshl_add_u64 v[246:247], s[0:1], 0, v[144:145]
	s_add_i32 m0, s13, 0x2000
	s_nop 0
	global_load_lds_dwordx4 v[246:247], off
	v_lshl_add_u64 v[246:247], s[10:11], 0, v[154:155]
	s_add_i32 m0, s42, 0x2000
	s_nop 0
	global_load_lds_dwordx4 v[246:247], off
	s_waitcnt lgkmcnt(10)
	v_mfma_f32_32x32x16_bf16 v[82:97], v[210:213], v[118:121], v[82:97]
	v_exp_f32_e32 v226, v79
	v_add_f32_e32 v66, v222, v66
	v_exp_f32_e32 v227, v80
	v_add_f32_e32 v66, v223, v66
	v_exp_f32_e32 v81, v81
	s_waitcnt lgkmcnt(9)
	v_mfma_f32_32x32x16_bf16 v[98:113], v[214:217], v[114:117], v[98:113]
	v_add_f32_e32 v66, v224, v66
	v_add_f32_e32 v66, v225, v66
	v_add_f32_e32 v66, v226, v66
	v_add_f32_e32 v66, v227, v66
	s_waitcnt lgkmcnt(8)
	v_mfma_f32_32x32x16_bf16 v[82:97], v[218:221], v[114:117], v[82:97]
	v_add_f32_e32 v130, v81, v66
	v_mov_b32_e32 v131, v130
	v_cvt_pk_bf16_f32 v66, v175, v177
	v_cvt_pk_bf16_f32 v67, v192, v195
	v_cvt_pk_bf16_f32 v68, v196, v199
	v_permlane32_swap_b32_e32 v130, v131
	v_cvt_pk_bf16_f32 v69, v200, v203
	v_permlane32_swap_b32_e32 v66, v68
	v_cvt_pk_bf16_f32 v70, v176, v193
	v_cvt_pk_bf16_f32 v71, v194, v197
	v_cvt_pk_bf16_f32 v72, v198, v201
	v_cvt_pk_bf16_f32 v73, v202, v204
	v_cvt_pk_bf16_f32 v74, v148, v149
	v_cvt_pk_bf16_f32 v75, v150, v151
	v_cvt_pk_bf16_f32 v76, v186, v187
	v_cvt_pk_bf16_f32 v77, v188, v189
	v_cvt_pk_bf16_f32 v78, v205, v222
	v_cvt_pk_bf16_f32 v79, v223, v224
	v_cvt_pk_bf16_f32 v80, v225, v226
	v_cvt_pk_bf16_f32 v81, v227, v81
	v_permlane32_swap_b32_e32 v67, v69
	v_permlane32_swap_b32_e32 v70, v72
	v_permlane32_swap_b32_e32 v71, v73
	v_permlane32_swap_b32_e32 v74, v76
	v_permlane32_swap_b32_e32 v75, v77
	v_permlane32_swap_b32_e32 v78, v80
	v_permlane32_swap_b32_e32 v79, v81
	ds_read_b64_tr_b16 v[204:205], v244 offset:0x200
	ds_read_b64_tr_b16 v[206:207], v244 offset:0xa00
	ds_read_b64_tr_b16 v[208:209], v244 offset:0x1200
	ds_read_b64_tr_b16 v[210:211], v244 offset:0x1a00
	ds_read_b64_tr_b16 v[212:213], v244 offset:0x2200
	ds_read_b64_tr_b16 v[214:215], v244 offset:0x2a00
	ds_read_b64_tr_b16 v[216:217], v244 offset:0x3200
	ds_read_b64_tr_b16 v[218:219], v244 offset:0x3a00
	s_waitcnt lgkmcnt(14)
	v_mfma_f32_32x32x16_bf16 v[18:33], v[66:69], v[228:231], v[18:33]
	v_max_f32_e32 v245, v99, v99
	v_max_f32_e32 v246, v98, v98
	v_max_f32_e32 v245, v246, v245
	v_max3_f32 v245, v245, v100, v101
	v_max3_f32 v245, v245, v102, v103
	v_max3_f32 v245, v245, v104, v105
	v_max3_f32 v245, v245, v106, v107
	v_max3_f32 v245, v245, v108, v109
	s_waitcnt lgkmcnt(12)
; #define SBAR() __builtin_amdgcn_sched_barrier(0)
; __device__ __forceinline__ void partialSM(f32x16& p0, f32x16& p1, float& m_reg, float& mn, float& alpha) {
;   constexpr float C = SCALE * 1.4426950408889634f;
;   float pmax = p0[0]; for (int r = 1; r < 16; ++r) pmax = fmaxf(pmax, p0[r]); for (int r = 0; r < 16; ++r) pmax = fmaxf(pmax, p1[r]);
;   { auto rr = __builtin_amdgcn_permlane32_swap(__float_as_uint(pmax), __float_as_uint(pmax), false, false);
;     pmax = fmaxf(__uint_as_float(rr[0]), __uint_as_float(rr[1])); }
;   if (__builtin_expect(__all(pmax - m_reg <= THR / SCALE), 1)) { mn = m_reg; alpha = 1.f; }
;   else { mn = fmaxf(m_reg, pmax); alpha = __builtin_amdgcn_exp2f((m_reg - mn) * C); m_reg = mn; }
;   float mnC = -mn * C;
;   for (int r = 0; r < 16; ++r) p0[r] = fmaf(p0[r], C, mnC); for (int r = 0; r < 16; ++r) p1[r] = fmaf(p1[r], C, mnC);
;   for (int r = 0; r < 16; ++r) p0[r] = __builtin_amdgcn_exp2f(p0[r]);
; }
; __device__ __forceinline__ void pv_d0(f32x16* o, int vb, bf16x8 pa0, bf16x8 pa1, bf16x8 pa2, bf16x8 pa3) {
;   VFrag fa, fb;
;   v_frag_read<0>(fa, vb);
;   asm volatile("s_waitcnt lgkmcnt(0)" ::: "memory"); SBAR();
;   v_frag_read<1>(fb, vb); SBAR();
;   pv_mma(o[0], fa, pa0, pa1, pa2, pa3); SBAR();
;   asm volatile("s_waitcnt lgkmcnt(0)" ::: "memory"); SBAR();
;   v_frag_read<2>(fa, vb); SBAR();
;   pv_mma(o[1], fb, pa0, pa1, pa2, pa3); SBAR();
;   asm volatile("s_waitcnt lgkmcnt(0)" ::: "memory"); SBAR();
;   v_frag_read<3>(fb, vb); SBAR();
;   pv_mma(o[2], fa, pa0, pa1, pa2, pa3); SBAR();
;   asm volatile("s_waitcnt lgkmcnt(0)" ::: "memory"); SBAR();
;   pv_mma(o[3], fb, pa0, pa1, pa2, pa3);
; }
	v_mfma_f32_32x32x16_bf16 v[18:33], v[70:73], v[232:235], v[18:33]
	v_max3_f32 v245, v245, v110, v111
	v_max3_f32 v245, v245, v112, v113
	v_max3_f32 v245, v245, v82, v83
	v_max3_f32 v245, v245, v84, v85
	v_max3_f32 v245, v245, v86, v87
	v_max3_f32 v245, v245, v88, v89
	v_max3_f32 v245, v245, v90, v91
	v_max3_f32 v245, v245, v92, v93
	s_waitcnt lgkmcnt(10)
	v_mfma_f32_32x32x16_bf16 v[18:33], v[74:77], v[236:239], v[18:33]
	v_max3_f32 v245, v245, v94, v95
	v_max3_f32 v245, v245, v96, v97
	v_mov_b32_e32 v246, v245
	s_nop 1
	v_permlane32_swap_b32_e32 v245, v246
	v_max_f32_e32 v246, v246, v246
	v_max_f32_e32 v245, v245, v245
	v_max_f32_e32 v245, v245, v246
	v_sub_f32_e32 v246, v245, v174
	s_waitcnt lgkmcnt(8)
	v_mfma_f32_32x32x16_bf16 v[18:33], v[78:81], v[240:243], v[18:33]
	v_cmp_ge_f32_e32 vcc, s63, v246
	v_max_f32_e32 v246, v174, v174
	v_max_f32_e32 v245, v246, v245
	v_sub_f32_e32 v246, v174, v245
	v_mul_f32_e32 v246, 0x3e38aa3b, v246
	v_exp_f32_e32 v246, v246
	s_cmp_eq_u64 vcc, exec
	s_cselect_b64 s[0:1], -1, 0
	v_cndmask_b32_e64 v132, v246, 1.0, s[0:1]
	ds_read_b64_tr_b16 v[228:229], v244 offset:0x400
	ds_read_b64_tr_b16 v[230:231], v244 offset:0xc00
	ds_read_b64_tr_b16 v[232:233], v244 offset:0x1400
	ds_read_b64_tr_b16 v[234:235], v244 offset:0x1c00
	ds_read_b64_tr_b16 v[236:237], v244 offset:0x2400
	ds_read_b64_tr_b16 v[238:239], v244 offset:0x2c00
	ds_read_b64_tr_b16 v[240:241], v244 offset:0x3400
	ds_read_b64_tr_b16 v[242:243], v244 offset:0x3c00
	v_cndmask_b32_e64 v133, v245, v174, s[0:1]
	v_mul_f32_e32 v148, 0xbe38aa3b, v133
	s_waitcnt lgkmcnt(14)
	v_mfma_f32_32x32x16_bf16 v[50:65], v[66:69], v[204:207], v[50:65]
	v_fmamk_f32 v98, v98, 0x3e38aa3b, v148
	v_fmamk_f32 v99, v99, 0x3e38aa3b, v148
	v_fmamk_f32 v100, v100, 0x3e38aa3b, v148
	v_fmamk_f32 v101, v101, 0x3e38aa3b, v148
	s_waitcnt lgkmcnt(12)
	v_mfma_f32_32x32x16_bf16 v[50:65], v[70:73], v[208:211], v[50:65]
	v_fmamk_f32 v102, v102, 0x3e38aa3b, v148
	v_fmamk_f32 v103, v103, 0x3e38aa3b, v148
	v_fmamk_f32 v104, v104, 0x3e38aa3b, v148
	v_fmamk_f32 v105, v105, 0x3e38aa3b, v148
	s_waitcnt lgkmcnt(10)
	v_mfma_f32_32x32x16_bf16 v[50:65], v[74:77], v[212:215], v[50:65]
	v_fmamk_f32 v106, v106, 0x3e38aa3b, v148
	v_fmamk_f32 v107, v107, 0x3e38aa3b, v148
	v_fmamk_f32 v108, v108, 0x3e38aa3b, v148
	v_fmamk_f32 v109, v109, 0x3e38aa3b, v148
	s_waitcnt lgkmcnt(8)
	v_mfma_f32_32x32x16_bf16 v[50:65], v[78:81], v[216:219], v[50:65]
	v_fmamk_f32 v110, v110, 0x3e38aa3b, v148
	v_fmamk_f32 v111, v111, 0x3e38aa3b, v148
	v_fmamk_f32 v112, v112, 0x3e38aa3b, v148
	v_fmamk_f32 v113, v113, 0x3e38aa3b, v148
	ds_read_b64_tr_b16 v[204:205], v244 offset:0x600
	ds_read_b64_tr_b16 v[206:207], v244 offset:0xe00
	ds_read_b64_tr_b16 v[208:209], v244 offset:0x1600
	ds_read_b64_tr_b16 v[210:211], v244 offset:0x1e00
	ds_read_b64_tr_b16 v[212:213], v244 offset:0x2600
	ds_read_b64_tr_b16 v[214:215], v244 offset:0x2e00
	ds_read_b64_tr_b16 v[216:217], v244 offset:0x3600
	ds_read_b64_tr_b16 v[218:219], v244 offset:0x3e00
	s_waitcnt lgkmcnt(14)
	v_mfma_f32_32x32x16_bf16 v[34:49], v[66:69], v[228:231], v[34:49]
	v_fmamk_f32 v82, v82, 0x3e38aa3b, v148
	v_fmamk_f32 v83, v83, 0x3e38aa3b, v148
	v_fmamk_f32 v84, v84, 0x3e38aa3b, v148
	v_fmamk_f32 v85, v85, 0x3e38aa3b, v148
	s_waitcnt lgkmcnt(12)
	v_mfma_f32_32x32x16_bf16 v[34:49], v[70:73], v[232:235], v[34:49]
	v_fmamk_f32 v86, v86, 0x3e38aa3b, v148
	v_fmamk_f32 v87, v87, 0x3e38aa3b, v148
	s_add_i32 s13, s36, 0xffff4000
	v_fmamk_f32 v149, v88, 0x3e38aa3b, v148
	s_waitcnt lgkmcnt(10)
	v_mfma_f32_32x32x16_bf16 v[34:49], v[74:77], v[236:239], v[34:49]
	v_fmamk_f32 v150, v89, 0x3e38aa3b, v148
	v_fmamk_f32 v151, v90, 0x3e38aa3b, v148
	v_fmamk_f32 v186, v91, 0x3e38aa3b, v148
	v_fmamk_f32 v187, v92, 0x3e38aa3b, v148
	s_waitcnt lgkmcnt(8)
	v_mfma_f32_32x32x16_bf16 v[34:49], v[78:81], v[240:243], v[34:49]
	v_fmamk_f32 v188, v93, 0x3e38aa3b, v148
	v_fmamk_f32 v189, v94, 0x3e38aa3b, v148
	v_exp_f32_e32 v192, v98
	v_exp_f32_e32 v193, v99
	v_exp_f32_e32 v194, v100
	v_exp_f32_e32 v195, v101
	s_waitcnt lgkmcnt(6)
	v_mfma_f32_32x32x16_bf16 v[2:17], v[66:69], v[204:207], v[2:17]
	v_exp_f32_e32 v196, v102
	v_exp_f32_e32 v197, v103
	v_exp_f32_e32 v198, v104
	v_exp_f32_e32 v199, v105
	s_waitcnt lgkmcnt(4)
	v_mfma_f32_32x32x16_bf16 v[2:17], v[70:73], v[208:211], v[2:17]
	v_exp_f32_e32 v200, v106
	v_exp_f32_e32 v201, v107
	v_exp_f32_e32 v202, v108
	v_exp_f32_e32 v203, v109
	v_exp_f32_e32 v204, v110
	v_exp_f32_e32 v205, v111
	s_waitcnt lgkmcnt(2)
	v_mfma_f32_32x32x16_bf16 v[2:17], v[74:77], v[212:215], v[2:17]
	v_exp_f32_e32 v206, v112
	v_exp_f32_e32 v207, v113
	v_fmamk_f32 v208, v95, 0x3e38aa3b, v148
	v_fmamk_f32 v209, v96, 0x3e38aa3b, v148
	v_fmac_f32_e32 v148, 0x3e38aa3b, v97
	s_waitcnt lgkmcnt(0)
	v_mfma_f32_32x32x16_bf16 v[2:17], v[78:81], v[216:219], v[2:17]
	v_add_u32_e32 v245, s101, v169
	v_add_u32_e32 v246, s101, v170
	v_add_u32_e32 v247, s101, v171
	v_add_u32_e32 v244, s101, v172
	v_cmp_gt_f32_e32 vcc, 1.0, v132
	s_cbranch_vccz .LBB0_774
	s_and_saveexec_b64 s[10:11], s[40:41]
	ds_write_b32 v162, v132 offset:128
	s_or_b64 exec, exec, s[10:11]
	s_waitcnt lgkmcnt(0)
	v_add_u32_e32 v67, s18, v140
	ds_read_b128 v[68:71], v67 offset:224
	ds_read_b128 v[72:75], v67 offset:192
	ds_read_b128 v[76:79], v67 offset:160
	ds_read_b128 v[134:137], v67 offset:128
	s_waitcnt lgkmcnt(0)
	v_pk_mul_f32 v[30:31], v[30:31], v[68:69]
	v_pk_mul_f32 v[26:27], v[26:27], v[72:73]
	v_pk_mul_f32 v[22:23], v[22:23], v[76:77]
	v_pk_mul_f32 v[32:33], v[32:33], v[70:71]
	v_pk_mul_f32 v[28:29], v[28:29], v[74:75]
	v_pk_mul_f32 v[24:25], v[24:25], v[78:79]
	v_pk_mul_f32 v[20:21], v[20:21], v[136:137]
	v_pk_mul_f32 v[18:19], v[18:19], v[134:135]
	v_pk_mul_f32 v[62:63], v[62:63], v[68:69]
	v_pk_mul_f32 v[58:59], v[58:59], v[72:73]
	v_pk_mul_f32 v[54:55], v[54:55], v[76:77]
	v_pk_mul_f32 v[64:65], v[64:65], v[70:71]
	v_pk_mul_f32 v[60:61], v[60:61], v[74:75]
	v_pk_mul_f32 v[56:57], v[56:57], v[78:79]
	v_pk_mul_f32 v[52:53], v[52:53], v[136:137]
	v_pk_mul_f32 v[50:51], v[50:51], v[134:135]
	v_pk_mul_f32 v[46:47], v[46:47], v[68:69]
	v_pk_mul_f32 v[42:43], v[42:43], v[72:73]
	v_pk_mul_f32 v[38:39], v[38:39], v[76:77]
	v_pk_mul_f32 v[48:49], v[48:49], v[70:71]
	v_pk_mul_f32 v[44:45], v[44:45], v[74:75]
	v_pk_mul_f32 v[40:41], v[40:41], v[78:79]
	v_pk_mul_f32 v[36:37], v[36:37], v[136:137]
	v_pk_mul_f32 v[34:35], v[34:35], v[134:135]
	v_pk_mul_f32 v[14:15], v[14:15], v[68:69]
	v_pk_mul_f32 v[10:11], v[10:11], v[72:73]
	v_pk_mul_f32 v[6:7], v[6:7], v[76:77]
	v_pk_mul_f32 v[16:17], v[16:17], v[70:71]
	v_pk_mul_f32 v[12:13], v[12:13], v[74:75]
	v_pk_mul_f32 v[8:9], v[8:9], v[78:79]
	v_pk_mul_f32 v[4:5], v[4:5], v[136:137]
	v_pk_mul_f32 v[2:3], v[2:3], v[134:135]
; #define SBAR() __builtin_amdgcn_sched_barrier(0)
; __device__ __forceinline__ void finishSM(f32x16& p0, f32x16& p1, float alpha, float& l_reg, bf16x8& pa0, bf16x8& pa1, bf16x8& pa2, bf16x8& pa3) {
;   for (int r = 0; r < 16; ++r) p1[r] = __builtin_amdgcn_exp2f(p1[r]);
;   float ps = 0; for (int r = 0; r < 16; ++r) ps += p0[r]; for (int r = 0; r < 16; ++r) ps += p1[r];
;   { auto rr = __builtin_amdgcn_permlane32_swap(__float_as_uint(ps), __float_as_uint(ps), false, false);
;     ps = __uint_as_float(rr[0]) + __uint_as_float(rr[1]); }
;   l_reg = l_reg * alpha + ps;
;     ...
;   PK4(p0, 0, pa0); PK4(p0, 8, pa1); PK4(p1, 0, pa2); PK4(p1, 8, pa3);
;     ...
; }
; __device__ __forceinline__ void kload(bf16x8 (&kf)[8], const char* Ks, int r32, int hi, int sb) {
; #pragma unroll
;   for (int d0 = 0; d0 < 4; ++d0) { const int cb = sb + (d0 * 16 + hi * 8) * 2;
;     kf[2 * d0] = *reinterpret_cast<const bf16x8*>(Ks + KSWZ(r32, cb)); kf[2 * d0 + 1] = *reinterpret_cast<const bf16x8*>(Ks + KSWZ(32 + r32, cb)); }
; }
; __device__ __forceinline__ void kmma(f32x16& p0, f32x16& p1, const bf16x8 (&kf)[8], const bf16x8* qr) {
;   asm volatile("s_waitcnt lgkmcnt(0)" ::: "memory"); SBAR();
;   p0 = f32x16{}; p1 = f32x16{};
; #pragma unroll
;   for (int d0 = 0; d0 < 4; ++d0) { p0 = __builtin_amdgcn_mfma_f32_32x32x16_bf16(kf[2 * d0], qr[d0], p0, 0, 0, 0); p1 = __builtin_amdgcn_mfma_f32_32x32x16_bf16(kf[2 * d0 + 1], qr[d0], p1, 0, 0, 0); }
; }
; __device__ __forceinline__ void qkt(f32x16& p0, f32x16& p1, const char* Ks, const bf16x8* qr, int r32, int hi, int sb) {
;   bf16x8 kf[8]; kload(kf, Ks, r32, hi, sb); SBAR(); kmma(p0, p1, kf, qr);
.LBB0_774:
	s_waitcnt vmcnt(4)
	s_barrier
	ds_read_b128 v[66:69], v245
	ds_read_b128 v[70:73], v245 offset:8192
	ds_read_b128 v[98:101], v246
	ds_read_b128 v[102:105], v246 offset:8192
	ds_read_b128 v[106:109], v247
	ds_read_b128 v[110:113], v247 offset:8192
	ds_read_b128 v[134:137], v244
	ds_read_b128 v[174:177], v244 offset:8192
	v_exp_f32_e32 v210, v82
	v_exp_f32_e32 v211, v83
	v_exp_f32_e32 v212, v84
	v_exp_f32_e32 v213, v85
	v_exp_f32_e32 v214, v86
	v_exp_f32_e32 v215, v87
	v_add_f32_e32 v216, 0, v192
	v_add_f32_e32 v216, v193, v216
	v_add_f32_e32 v216, v194, v216
	v_add_f32_e32 v216, v195, v216
	v_exp_f32_e32 v149, v149
	v_exp_f32_e32 v150, v150
	v_exp_f32_e32 v151, v151
	v_exp_f32_e32 v186, v186
	v_exp_f32_e32 v187, v187
	v_exp_f32_e32 v188, v188
	s_waitcnt lgkmcnt(7)
	v_mfma_f32_32x32x16_bf16 v[82:97], v[66:69], v[126:129], 0
	s_and_b32 s46, s13, 0xc000
	v_exp_f32_e32 v189, v189
	v_add_u32_e32 v244, s46, v164
	v_exp_f32_e32 v208, v208
	ds_read_b64_tr_b16 v[228:229], v244 offset:0
	v_exp_f32_e32 v209, v209
	ds_read_b64_tr_b16 v[230:231], v244 offset:0x800
	v_exp_f32_e32 v148, v148
	ds_read_b64_tr_b16 v[232:233], v244 offset:0x1000
	ds_read_b64_tr_b16 v[234:235], v244 offset:0x1800
	ds_read_b64_tr_b16 v[236:237], v244 offset:0x2000
	s_waitcnt lgkmcnt(11)
	v_mfma_f32_32x32x16_bf16 v[66:81], v[70:73], v[126:129], 0
	ds_read_b64_tr_b16 v[238:239], v244 offset:0x2800
	v_add_f32_e32 v255, v196, v216
	ds_read_b64_tr_b16 v[240:241], v244 offset:0x3000
	v_add_f32_e32 v255, v197, v255
	ds_read_b64_tr_b16 v[242:243], v244 offset:0x3800
	v_add_f32_e32 v255, v198, v255
	s_add_i32 s46, s12, 3
	v_add_f32_e32 v255, v199, v255
	s_cmpk_lt_u32 s12, 0x7d
	v_add_f32_e32 v255, v200, v255
	s_cselect_b64 s[42:43], -1, 0
	s_and_b64 s[44:45], s[42:43], exec
	s_waitcnt lgkmcnt(13)
	v_mfma_f32_32x32x16_bf16 v[82:97], v[98:101], v[122:125], v[82:97]
	s_cselect_b32 s44, 0, 0xffffff80
	v_add_f32_e32 v255, v201, v255
	s_add_i32 s58, s46, s44
	v_add_f32_e32 v255, v202, v255
	s_and_b64 s[42:43], s[42:43], exec
	v_add_f32_e32 v255, v203, v255
	s_cselect_b32 s43, s9, s30
	v_add_f32_e32 v255, v204, v255
	s_cselect_b32 s42, s8, s26
	s_lshl_b64 s[44:45], s[58:59], 17
	s_lshl_b64 s[42:43], s[42:43], 11
	s_waitcnt lgkmcnt(12)
	v_mfma_f32_32x32x16_bf16 v[66:81], v[102:105], v[122:125], v[66:81]
	s_add_u32 s44, s44, s42
	v_add_f32_e32 v255, v205, v255
	s_addc_u32 s45, s45, s43
	v_add_f32_e32 v255, v206, v255
	s_add_u32 s42, s20, s44
	v_add_f32_e32 v255, v207, v255
	s_addc_u32 s43, s21, s45
	v_add_f32_e32 v255, v210, v255
	s_add_u32 s44, s22, s44
	v_add_f32_e32 v255, v211, v255
	s_mul_i32 s47, s46, 0xab
	s_addc_u32 s45, s23, s45
	s_waitcnt lgkmcnt(11)
	v_mfma_f32_32x32x16_bf16 v[82:97], v[106:109], v[118:121], v[82:97]
	s_bfe_u32 s47, s47, 0x70009
	v_add_f32_e32 v255, v212, v255
	s_mul_i32 s47, s47, 3
	v_add_f32_e32 v255, v213, v255
	s_sub_i32 s46, s46, s47
	v_add_f32_e32 v255, v214, v255
	s_and_b32 s46, s46, 0xff
	v_add_f32_e32 v255, v215, v255
	s_lshl_b32 s46, s46, 14
	s_mov_b32 s101, s46
	s_add_i32 s46, s46, s27
	s_and_b32 s47, s36, 0xc000
	s_add_i32 s47, s47, s31
	s_waitcnt lgkmcnt(10)
	v_mfma_f32_32x32x16_bf16 v[66:81], v[110:113], v[118:121], v[66:81]
	v_add_f32_e32 v255, v149, v255
	v_add_f32_e32 v255, v150, v255
	v_add_f32_e32 v255, v151, v255
	v_add_f32_e32 v255, v186, v255
	v_add_f32_e32 v255, v187, v255
	s_waitcnt lgkmcnt(9)
	v_mfma_f32_32x32x16_bf16 v[82:97], v[134:137], v[114:117], v[82:97]
	v_add_f32_e32 v255, v188, v255
	v_add_f32_e32 v255, v189, v255
	v_add_f32_e32 v255, v208, v255
	v_add_f32_e32 v255, v209, v255
	v_add_f32_e32 v99, v148, v255
	s_cmpk_gt_u32 s12, 0x80
	s_cselect_b64 s[10:11], -1, 0
	s_and_b64 vcc, exec, s[10:11]
	s_cbranch_vccnz .LBB0_776
	v_lshl_add_u64 v[246:247], s[42:43], 0, v[146:147]
	s_mov_b32 m0, s46
	s_nop 0
	global_load_lds_dwordx4 v[246:247], off
	v_lshl_add_u64 v[246:247], s[44:45], 0, v[142:143]
	s_mov_b32 m0, s47
	s_nop 0
	global_load_lds_dwordx4 v[246:247], off
	v_lshl_add_u64 v[246:247], s[42:43], 0, v[144:145]
	s_add_i32 m0, s46, 0x2000
	s_nop 0
	global_load_lds_dwordx4 v[246:247], off
	v_lshl_add_u64 v[246:247], s[44:45], 0, v[154:155]
	s_add_i32 m0, s47, 0x2000
	s_nop 0
	global_load_lds_dwordx4 v[246:247], off
